# phase 1 row loop: scale/shift chunks 1..3 loaded together with chunk 0 and waited with counted vmcnt (no vmcnt(0) blocking on the next row's loads)
# baseline (speedup 1.0000x reference)
; DI unsigned pk2(float a, float b) { f32x2 v = {a, b}; bf16x2_t r = __builtin_convertvector(v, bf16x2_t); return __builtin_bit_cast(unsigned, r); }
; template <int MODE>
; DI void norm_rows(const Params& p) {
;     ...
;     for (int row0 = gw; row0 < nrows; row0 += 2 * NGW) {
;         const float* src[2]; int mb[2]; f32x4 v[2][4]; float s[2];
; #pragma unroll
;         for (int u = 0; u < 2; ++u) {
;             const int row = row0 + u * NGW < nrows ? row0 + u * NGW : row0;
;             if (MODE == 0) { if (row < NLAT) { src[u] = p.x + (size_t)row * DM; mb[u] = row >> 12; } else { src[u] = p.ctx + (size_t)(row - NLAT) * DM; mb[u] = 16; } }
;             else { src[u] = p.out + (size_t)row * DM; mb[u] = row >> 12; }
; #pragma unroll
;             for (int j = 0; j < 4; ++j) v[u][j] = *(const f32x4*)(src[u] + 4 * lane + 256 * j);
;         }
; #pragma unroll
;         for (int u = 0; u < 2; ++u) {
;             const int row = row0 + u * NGW;
;             if (row >= nrows) break;
;             s[u] = 0.f;
; #pragma unroll
;             for (int j = 0; j < 4; ++j) s[u] += (v[u][j].x * v[u][j].x + v[u][j].y * v[u][j].y) + (v[u][j].z * v[u][j].z + v[u][j].w * v[u][j].w);
;             const float rstd = rsqrtf(wave_sum(s[u]) * (1.f / DM) + EPS);
;             if (MODE == 2) {
;                 float* dst = p.out + (size_t)row * DM;
; #pragma unroll
;                 for (int j = 0; j < 4; ++j) *(f32x4*)(dst + 4 * lane + 256 * j) = v[u][j] * rstd * gn[j];
;             } else {
;                 const float* mrow = modp + (size_t)mb[u] * NMODC + (MODE == 0 ? 0 : 3072);
;                 bf16_t* dst = (bf16_t*)(p.ws + OFF_A) + (MODE == 0 ? (size_t)0 : (size_t)NLAT * 1024) + (size_t)row * DM;
; #pragma unroll
;                 for (int j = 0; j < 4; ++j) {
;                     const f32x4 sh = *(const f32x4*)(mrow + 4 * lane + 256 * j), scl = *(const f32x4*)(mrow + 1024 + 4 * lane + 256 * j);
;                     const f32x4 y = (v[u][j] * rstd * gn[j]) * (scl + 1.f) + sh;
;                     u32x2 o; o.x = pk2(y.x, y.y); o.y = pk2(y.z, y.w);
;                     *(u32x2*)(dst + 4 * lane + 256 * j) = o;
.LBB0_139:
	v_cmp_lt_i32_e32 vcc, s22, v16
	s_and_saveexec_b64 s[4:5], vcc
	s_xor_b64 s[4:5], exec, s[4:5]
	v_add_u32_e32 v18, 0xffff0000, v16
	v_mov_b32_e32 v19, v49
	v_lshlrev_b64 v[18:19], 12, v[18:19]
	v_lshl_add_u64 v[18:19], s[40:41], 0, v[18:19]
	s_or_saveexec_b64 s[4:5], s[4:5]
	v_mov_b64_e32 v[20:21], 0x60000
	v_ashrrev_i32_e32 v17, 31, v16
	s_xor_b64 exec, exec, s[4:5]
	v_lshlrev_b64 v[18:19], 12, v[16:17]
	v_ashrrev_i32_e32 v20, 12, v16
	v_lshl_add_u64 v[18:19], s[36:37], 0, v[18:19]
	v_mul_hi_i32_i24_e32 v21, 0x6000, v20
	v_mul_i32_i24_e32 v20, 0x6000, v20
	s_or_b64 exec, exec, s[4:5]
	v_lshl_add_u64 v[18:19], v[18:19], 0, v[48:49]
	global_load_dwordx4 v[44:47], v[18:19], off
	global_load_dwordx4 v[40:43], v[18:19], off offset:1024
	global_load_dwordx4 v[36:39], v[18:19], off offset:2048
	global_load_dwordx4 v[24:27], v[18:19], off offset:3072
	v_add_u32_e32 v52, s19, v16
	v_cmp_gt_i32_e32 vcc, s18, v52
	s_nop 1
	v_cndmask_b32_e32 v22, v16, v52, vcc
	v_cmp_lt_i32_e64 s[4:5], s22, v22
	s_and_saveexec_b64 s[38:39], s[4:5]
	s_xor_b64 s[4:5], exec, s[38:39]
	v_add_u32_e32 v18, 0xffff0000, v22
	v_mov_b32_e32 v19, v49
	v_lshlrev_b64 v[18:19], 12, v[18:19]
	v_lshl_add_u64 v[18:19], s[40:41], 0, v[18:19]
	s_or_saveexec_b64 s[4:5], s[4:5]
	v_mov_b64_e32 v[54:55], 0x60000
	s_xor_b64 exec, exec, s[4:5]
	v_ashrrev_i32_e32 v23, 31, v22
	v_lshlrev_b64 v[18:19], 12, v[22:23]
	v_ashrrev_i32_e32 v22, 12, v22
	v_lshl_add_u64 v[18:19], s[36:37], 0, v[18:19]
	v_mul_hi_i32_i24_e32 v55, 0x6000, v22
	v_mul_i32_i24_e32 v54, 0x6000, v22
	s_or_b64 exec, exec, s[4:5]
	v_lshl_add_u64 v[20:21], s[12:13], 0, v[20:21]
	v_lshl_add_u64 v[72:73], v[20:21], 0, v[48:49]
	v_add_co_u32_e64 v20, s[4:5], s24, v72
	s_waitcnt vmcnt(3)
	v_pk_mul_f32 v[22:23], v[44:45], v[44:45]
	v_addc_co_u32_e64 v21, s[4:5], 0, v73, s[4:5]
	global_load_dwordx4 v[64:67], v[72:73], off
	global_load_dwordx4 v[68:71], v[20:21], off
	global_load_dwordx4 v[200:203], v[20:21], off offset:1024
	global_load_dwordx4 v[204:207], v[72:73], off offset:1024
	global_load_dwordx4 v[208:211], v[20:21], off offset:2048
	global_load_dwordx4 v[212:215], v[72:73], off offset:2048
	global_load_dwordx4 v[216:219], v[20:21], off offset:3072
	global_load_dwordx4 v[220:223], v[72:73], off offset:3072
	v_pk_mul_f32 v[20:21], v[46:47], v[46:47]
	v_lshlrev_b64 v[74:75], 11, v[16:17]
	v_pk_mov_b32 v[28:29], v[22:23], v[20:21] op_sel:[1,0]
	v_mov_b32_e32 v23, v21
	v_pk_add_f32 v[20:21], v[28:29], v[22:23]
	s_waitcnt vmcnt(10)
	v_pk_mul_f32 v[22:23], v[42:43], v[42:43]
	v_pk_mul_f32 v[28:29], v[40:41], v[40:41]
	v_pk_add_f32 v[20:21], v[20:21], v[20:21] op_sel:[0,1] op_sel_hi:[1,0]
	v_pk_mov_b32 v[30:31], v[28:29], v[22:23] op_sel:[1,0]
	v_mov_b32_e32 v29, v23
	v_pk_add_f32 v[22:23], v[30:31], v[28:29]
	s_waitcnt vmcnt(8)
	v_mul_f32_e32 v28, v24, v24
	v_mul_f32_e32 v29, v25, v25
	v_pk_add_f32 v[22:23], v[22:23], v[22:23] op_sel:[0,1] op_sel_hi:[1,0]
	v_mov_b32_e32 v21, v28
	v_mov_b32_e32 v23, v29
	v_pk_add_f32 v[20:21], v[20:21], v[22:23]
	v_mul_f32_e32 v22, v37, v37
	v_mul_f32_e32 v28, v39, v39
	v_mul_f32_e32 v30, v26, v26
	v_mul_f32_e32 v31, v27, v27
	v_pk_fma_f32 v[22:23], v[36:37], v[36:37], v[22:23] op_sel_hi:[1,1,0]
	v_pk_fma_f32 v[28:29], v[38:39], v[38:39], v[28:29] op_sel_hi:[1,1,0]
	v_mov_b32_e32 v23, v30
	v_mov_b32_e32 v29, v31
	v_pk_add_f32 v[22:23], v[22:23], v[28:29]
	v_lshl_add_u64 v[18:19], v[18:19], 0, v[48:49]
	v_pk_add_f32 v[20:21], v[20:21], v[22:23]
	v_lshl_add_u64 v[74:75], v[50:51], 0, v[74:75]
	v_add_f32_e32 v20, v20, v21
	s_nop 1
	v_mov_b32_dpp v21, v20 quad_perm:[1,0,3,2] row_mask:0xf bank_mask:0xf
	global_load_dwordx4 v[32:35], v[18:19], off
	global_load_dwordx4 v[28:31], v[18:19], off offset:1024
	v_lshl_add_u64 v[76:77], v[72:73], 0, s[16:17]
	s_waitcnt lgkmcnt(0)
	v_add_f32_e32 v20, v20, v21
	s_nop 1
	v_mov_b32_dpp v21, v20 quad_perm:[2,3,0,1] row_mask:0xf bank_mask:0xf
	s_waitcnt lgkmcnt(0)
	v_add_f32_e32 v20, v20, v21
	s_nop 1
	v_mov_b32_dpp v21, v20 row_half_mirror row_mask:0xf bank_mask:0xf
	s_waitcnt lgkmcnt(0)
	v_add_f32_e32 v20, v20, v21
	s_nop 1
	v_mov_b32_dpp v21, v20 row_ror:8 row_mask:0xf bank_mask:0xf
	s_waitcnt lgkmcnt(0)
	v_add_f32_e32 v20, v20, v21
	ds_bpermute_b32 v21, v60, v20
	s_waitcnt lgkmcnt(0)
	v_add_f32_e32 v20, v20, v21
	ds_bpermute_b32 v21, v61, v20
	s_waitcnt lgkmcnt(0)
	v_add_f32_e32 v16, v20, v21
	v_fmamk_f32 v16, v16, 0x3a800000, v62
	v_mul_f32_e32 v17, 0x4b800000, v16
	v_cmp_gt_f32_e64 s[4:5], s23, v16
	s_waitcnt vmcnt(8)
	v_pk_add_f32 v[70:71], v[70:71], 1.0 op_sel_hi:[1,0]
	v_cndmask_b32_e64 v16, v16, v17, s[4:5]
	v_rsq_f32_e32 v53, v16
	v_pk_add_f32 v[68:69], v[68:69], 1.0 op_sel_hi:[1,0]
	global_load_dwordx4 v[20:23], v[18:19], off offset:2048
	s_nop 0
	global_load_dwordx4 v[16:19], v[18:19], off offset:3072
	v_mul_f32_e32 v63, 0x45800000, v53
	v_cndmask_b32_e64 v78, v53, v63, s[4:5]
	v_pk_mul_f32 v[46:47], v[46:47], v[78:79] op_sel_hi:[1,0]
	v_pk_mul_f32 v[44:45], v[44:45], v[78:79] op_sel_hi:[1,0]
	v_pk_mul_f32 v[46:47], v[2:3], v[46:47]
	v_pk_mul_f32 v[44:45], v[0:1], v[44:45]
	v_pk_fma_f32 v[46:47], v[70:71], v[46:47], v[66:67]
	v_pk_fma_f32 v[44:45], v[68:69], v[44:45], v[64:65]
	v_pk_mul_f32 v[42:43], v[42:43], v[78:79] op_sel_hi:[1,0]
	v_cvt_pk_bf16_f32 v44, v44, v45
	v_cvt_pk_bf16_f32 v45, v46, v47
	global_store_dwordx2 v[74:75], v[44:45], off
	v_pk_mul_f32 v[40:41], v[40:41], v[78:79] op_sel_hi:[1,0]
	v_pk_mul_f32 v[42:43], v[6:7], v[42:43]
	v_pk_mul_f32 v[40:41], v[4:5], v[40:41]
	v_pk_mul_f32 v[38:39], v[38:39], v[78:79] op_sel_hi:[1,0]
	v_pk_mul_f32 v[36:37], v[36:37], v[78:79] op_sel_hi:[1,0]
	v_pk_mul_f32 v[38:39], v[10:11], v[38:39]
	v_pk_mul_f32 v[36:37], v[8:9], v[36:37]
	v_pk_mul_f32 v[26:27], v[26:27], v[78:79] op_sel_hi:[1,0]
	v_pk_mul_f32 v[24:25], v[24:25], v[78:79] op_sel_hi:[1,0]
	v_pk_mul_f32 v[26:27], v[14:15], v[26:27]
	v_pk_mul_f32 v[24:25], v[12:13], v[24:25]
	s_waitcnt vmcnt(10)
; DI unsigned pk2(float a, float b) { f32x2 v = {a, b}; bf16x2_t r = __builtin_convertvector(v, bf16x2_t); return __builtin_bit_cast(unsigned, r); }
; template <int MODE>
; DI void norm_rows(const Params& p) {
;     ...
;         for (int u = 0; u < 2; ++u) {
;             const int row = row0 + u * NGW;
;             if (row >= nrows) break;
;             s[u] = 0.f;
; #pragma unroll
;             for (int j = 0; j < 4; ++j) s[u] += (v[u][j].x * v[u][j].x + v[u][j].y * v[u][j].y) + (v[u][j].z * v[u][j].z + v[u][j].w * v[u][j].w);
;             const float rstd = rsqrtf(wave_sum(s[u]) * (1.f / DM) + EPS);
;             if (MODE == 2) {
;                 float* dst = p.out + (size_t)row * DM;
; #pragma unroll
;                 for (int j = 0; j < 4; ++j) *(f32x4*)(dst + 4 * lane + 256 * j) = v[u][j] * rstd * gn[j];
;             } else {
;                 const float* mrow = modp + (size_t)mb[u] * NMODC + (MODE == 0 ? 0 : 3072);
;                 bf16_t* dst = (bf16_t*)(p.ws + OFF_A) + (MODE == 0 ? (size_t)0 : (size_t)NLAT * 1024) + (size_t)row * DM;
; #pragma unroll
;                 for (int j = 0; j < 4; ++j) {
;                     const f32x4 sh = *(const f32x4*)(mrow + 4 * lane + 256 * j), scl = *(const f32x4*)(mrow + 1024 + 4 * lane + 256 * j);
;                     const f32x4 y = (v[u][j] * rstd * gn[j]) * (scl + 1.f) + sh;
;                     u32x2 o; o.x = pk2(y.x, y.y); o.y = pk2(y.z, y.w);
;                     *(u32x2*)(dst + 4 * lane + 256 * j) = o;
	v_pk_add_f32 v[46:47], v[202:203], 1.0 op_sel_hi:[1,0]
	v_pk_add_f32 v[44:45], v[200:201], 1.0 op_sel_hi:[1,0]
	s_waitcnt vmcnt(9)
	v_pk_fma_f32 v[42:43], v[46:47], v[42:43], v[206:207]
	v_pk_fma_f32 v[40:41], v[44:45], v[40:41], v[204:205]
	s_nop 0
	v_cvt_pk_bf16_f32 v40, v40, v41
	v_cvt_pk_bf16_f32 v41, v42, v43
	global_store_dwordx2 v[74:75], v[40:41], off offset:512
	s_waitcnt vmcnt(9)
	v_pk_add_f32 v[42:43], v[210:211], 1.0 op_sel_hi:[1,0]
	v_pk_add_f32 v[40:41], v[208:209], 1.0 op_sel_hi:[1,0]
	s_waitcnt vmcnt(8)
	v_pk_fma_f32 v[38:39], v[42:43], v[38:39], v[214:215]
	v_pk_fma_f32 v[36:37], v[40:41], v[36:37], v[212:213]
	s_nop 0
	v_cvt_pk_bf16_f32 v36, v36, v37
	v_cvt_pk_bf16_f32 v37, v38, v39
	global_store_dwordx2 v[74:75], v[36:37], off offset:1024
	s_waitcnt vmcnt(8)
	v_pk_add_f32 v[38:39], v[218:219], 1.0 op_sel_hi:[1,0]
	v_pk_add_f32 v[36:37], v[216:217], 1.0 op_sel_hi:[1,0]
	s_waitcnt vmcnt(7)
	v_pk_fma_f32 v[26:27], v[38:39], v[26:27], v[222:223]
	v_pk_fma_f32 v[24:25], v[36:37], v[24:25], v[220:221]
	s_nop 0
	v_cvt_pk_bf16_f32 v24, v24, v25
	v_cvt_pk_bf16_f32 v25, v26, v27
	global_store_dwordx2 v[74:75], v[24:25], off offset:1536
	s_and_saveexec_b64 s[4:5], vcc
	s_cbranch_execz .LBB0_138
	s_waitcnt vmcnt(4)
	v_lshl_add_u64 v[24:25], s[12:13], 0, v[54:55]
	v_lshl_add_u64 v[40:41], v[24:25], 0, v[48:49]
	v_add_co_u32_e32 v24, vcc, s24, v40
	v_pk_mul_f32 v[42:43], v[34:35], v[34:35]
	s_nop 0
	v_addc_co_u32_e32 v25, vcc, 0, v41, vcc
	global_load_dwordx4 v[224:227], v[24:25], off offset:1024
	global_load_dwordx4 v[228:231], v[40:41], off offset:1024
	global_load_dwordx4 v[232:235], v[24:25], off offset:2048
	global_load_dwordx4 v[236:239], v[40:41], off offset:2048
	global_load_dwordx4 v[240:243], v[24:25], off offset:3072
	global_load_dwordx4 v[244:247], v[40:41], off offset:3072
	global_load_dwordx4 v[24:27], v[24:25], off
	s_nop 0
	global_load_dwordx4 v[36:39], v[40:41], off
	v_pk_mul_f32 v[44:45], v[32:33], v[32:33]
	v_mul_f32_e32 v53, v18, v18
	v_pk_mov_b32 v[46:47], v[44:45], v[42:43] op_sel:[1,0]
	v_mov_b32_e32 v45, v43
	v_pk_add_f32 v[42:43], v[46:47], v[44:45]
	v_pk_mul_f32 v[44:45], v[30:31], v[30:31]
	v_pk_mul_f32 v[46:47], v[28:29], v[28:29]
	v_pk_add_f32 v[42:43], v[42:43], v[42:43] op_sel:[0,1] op_sel_hi:[1,0]
	v_pk_mov_b32 v[54:55], v[46:47], v[44:45] op_sel:[1,0]
	v_mov_b32_e32 v47, v45
	v_pk_add_f32 v[44:45], v[54:55], v[46:47]
	v_mul_f32_e32 v46, v16, v16
	v_mul_f32_e32 v47, v17, v17
	v_pk_add_f32 v[44:45], v[44:45], v[44:45] op_sel:[0,1] op_sel_hi:[1,0]
	v_mov_b32_e32 v43, v46
	v_mov_b32_e32 v45, v47
	v_pk_add_f32 v[42:43], v[42:43], v[44:45]
	v_mul_f32_e32 v44, v21, v21
	v_mul_f32_e32 v46, v23, v23
	v_mul_f32_e32 v54, v19, v19
	v_pk_fma_f32 v[44:45], v[20:21], v[20:21], v[44:45] op_sel_hi:[1,1,0]
	v_pk_fma_f32 v[46:47], v[22:23], v[22:23], v[46:47] op_sel_hi:[1,1,0]
	v_mov_b32_e32 v45, v53
	v_mov_b32_e32 v47, v54
	v_pk_add_f32 v[44:45], v[44:45], v[46:47]
	v_ashrrev_i32_e32 v53, 31, v52
	v_pk_add_f32 v[42:43], v[42:43], v[44:45]
	v_lshl_add_u64 v[44:45], v[40:41], 0, s[16:17]
	v_add_f32_e32 v42, v42, v43
	s_nop 1
	v_mov_b32_dpp v43, v42 quad_perm:[1,0,3,2] row_mask:0xf bank_mask:0xf
	s_waitcnt lgkmcnt(0)
	v_add_f32_e32 v42, v42, v43
	s_nop 1
	v_mov_b32_dpp v43, v42 quad_perm:[2,3,0,1] row_mask:0xf bank_mask:0xf
	s_waitcnt lgkmcnt(0)
	v_add_f32_e32 v42, v42, v43
	s_nop 1
	v_mov_b32_dpp v43, v42 row_half_mirror row_mask:0xf bank_mask:0xf
	s_waitcnt lgkmcnt(0)
	v_add_f32_e32 v42, v42, v43
	s_nop 1
	v_mov_b32_dpp v43, v42 row_ror:8 row_mask:0xf bank_mask:0xf
	s_waitcnt lgkmcnt(0)
	v_add_f32_e32 v42, v42, v43
	ds_bpermute_b32 v43, v60, v42
	s_waitcnt lgkmcnt(0)
	v_add_f32_e32 v42, v42, v43
	ds_bpermute_b32 v43, v61, v42
	s_waitcnt lgkmcnt(0)
	v_add_f32_e32 v42, v42, v43
	v_fmamk_f32 v42, v42, 0x3a800000, v62
	v_mul_f32_e32 v43, 0x4b800000, v42
	v_cmp_gt_f32_e32 vcc, s23, v42
	s_waitcnt vmcnt(1)
	v_pk_add_f32 v[26:27], v[26:27], 1.0 op_sel_hi:[1,0]
	v_cndmask_b32_e32 v42, v42, v43, vcc
	v_rsq_f32_e32 v46, v42
	v_pk_add_f32 v[24:25], v[24:25], 1.0 op_sel_hi:[1,0]
	v_lshlrev_b64 v[42:43], 11, v[52:53]
	v_lshl_add_u64 v[42:43], v[50:51], 0, v[42:43]
	v_mul_f32_e32 v47, 0x45800000, v46
	v_cndmask_b32_e32 v46, v46, v47, vcc
	v_pk_mul_f32 v[34:35], v[34:35], v[46:47] op_sel_hi:[1,0]
	v_pk_mul_f32 v[32:33], v[32:33], v[46:47] op_sel_hi:[1,0]
	v_pk_mul_f32 v[34:35], v[2:3], v[34:35]
	v_pk_mul_f32 v[32:33], v[0:1], v[32:33]
	s_waitcnt vmcnt(0)
	v_pk_fma_f32 v[26:27], v[26:27], v[34:35], v[38:39]
	v_pk_fma_f32 v[24:25], v[24:25], v[32:33], v[36:37]
	v_pk_mul_f32 v[30:31], v[30:31], v[46:47] op_sel_hi:[1,0]
	v_cvt_pk_bf16_f32 v24, v24, v25
	v_cvt_pk_bf16_f32 v25, v26, v27
	global_store_dwordx2 v[42:43], v[24:25], off
	v_pk_mul_f32 v[28:29], v[28:29], v[46:47] op_sel_hi:[1,0]
	v_pk_mul_f32 v[30:31], v[6:7], v[30:31]
	v_pk_mul_f32 v[28:29], v[4:5], v[28:29]
	v_pk_mul_f32 v[22:23], v[22:23], v[46:47] op_sel_hi:[1,0]
	v_pk_mul_f32 v[20:21], v[20:21], v[46:47] op_sel_hi:[1,0]
	v_pk_mul_f32 v[22:23], v[10:11], v[22:23]
	v_pk_mul_f32 v[20:21], v[8:9], v[20:21]
	v_pk_mul_f32 v[18:19], v[18:19], v[46:47] op_sel_hi:[1,0]
	v_pk_mul_f32 v[16:17], v[16:17], v[46:47] op_sel_hi:[1,0]
	v_pk_mul_f32 v[18:19], v[14:15], v[18:19]
	v_pk_mul_f32 v[16:17], v[12:13], v[16:17]
	v_pk_add_f32 v[26:27], v[226:227], 1.0 op_sel_hi:[1,0]
	v_pk_add_f32 v[24:25], v[224:225], 1.0 op_sel_hi:[1,0]
	v_pk_fma_f32 v[26:27], v[26:27], v[30:31], v[230:231]
	v_pk_fma_f32 v[24:25], v[24:25], v[28:29], v[228:229]
	s_nop 0
	v_cvt_pk_bf16_f32 v24, v24, v25
	v_cvt_pk_bf16_f32 v25, v26, v27
	global_store_dwordx2 v[42:43], v[24:25], off offset:512
	v_pk_add_f32 v[26:27], v[234:235], 1.0 op_sel_hi:[1,0]
	v_pk_add_f32 v[24:25], v[232:233], 1.0 op_sel_hi:[1,0]
	v_pk_fma_f32 v[22:23], v[26:27], v[22:23], v[238:239]
	v_pk_fma_f32 v[20:21], v[24:25], v[20:21], v[236:237]
	s_nop 0
	v_cvt_pk_bf16_f32 v20, v20, v21
	v_cvt_pk_bf16_f32 v21, v22, v23
	global_store_dwordx2 v[42:43], v[20:21], off offset:1024
	v_pk_add_f32 v[22:23], v[242:243], 1.0 op_sel_hi:[1,0]
	v_pk_add_f32 v[20:21], v[240:241], 1.0 op_sel_hi:[1,0]
	v_pk_fma_f32 v[18:19], v[22:23], v[18:19], v[246:247]
	v_pk_fma_f32 v[16:17], v[20:21], v[16:17], v[244:245]
	s_nop 0
	v_cvt_pk_bf16_f32 v16, v16, v17
	v_cvt_pk_bf16_f32 v17, v18, v19
	global_store_dwordx2 v[42:43], v[16:17], off offset:1536
	s_branch .LBB0_138
